# seam waiters poll the grid-level generation word directly (one hop less per seam)
# baseline (speedup 1.0000x reference)
; DI unsigned xb_ld(unsigned* p) { return __hip_atomic_load(p, __ATOMIC_RELAXED, __HIP_MEMORY_SCOPE_AGENT); }
; DI unsigned xb_add(unsigned* p, unsigned v) { return __hip_atomic_fetch_add(p, v, __ATOMIC_RELAXED, __HIP_MEMORY_SCOPE_AGENT); }
; #define XB_SPIN(cond, bar) do { unsigned _sp = 0; while (cond) { __builtin_amdgcn_s_sleep(1); \
;     if ((++_sp & 255u) == 0u) { if (xb_ld(&(bar)[XB_TMO])) break; if (_sp > XB_SPIN_CAP) { atomicAdd(&(bar)[XB_TMO], 1u); break; } } } } while (0)
; DI void xcd_barrier(const XcdBarrier& b) {
;     ...
;     const unsigned old = xb_add(&bar[XB_XSUB(b.x)], 1u);
;     const unsigned gen = old / nloc;
;     if (old + 1u == (gen + 1u) * nloc) {
;       __builtin_amdgcn_fence(__ATOMIC_RELEASE, "agent");
;       asm volatile("s_waitcnt vmcnt(0)" ::: "memory");
;       const unsigned og = xb_add(&bar[XB_TOP], 1u);
;       const unsigned tg = og / nx;
;       if (og + 1u == (tg + 1u) * nx) xb_add(&bar[XB_TOPGEN], 1u);
;       else XB_SPIN(xb_ld(&bar[XB_TOPGEN]) == tg, bar);
;       __builtin_amdgcn_fence(__ATOMIC_ACQUIRE, "agent");
;       xb_add(&bar[XB_XGEN(b.x)], 1u);
;       asm volatile("s_waitcnt vmcnt(0)" ::: "memory");
;     } else {
;       XB_SPIN(xb_ld(&bar[XB_XGEN(b.x)]) == gen, bar);
.LBB0_109:
	s_or_b64 exec, exec, s[2:3]
	v_cvt_f32_u32_e32 v5, v3
	s_waitcnt vmcnt(0)
	v_readfirstlane_b32 s2, v4
	v_sub_u32_e32 v4, 0, v3
	v_rcp_iflag_f32_e32 v5, v5
	v_add_u32_e32 v6, s2, v0
	v_mul_f32_e32 v5, 0x4f7ffffe, v5
	v_cvt_u32_f32_e32 v5, v5
	v_mul_lo_u32 v0, v4, v5
	v_mul_hi_u32 v0, v5, v0
	v_add_u32_e32 v0, v5, v0
	v_mul_hi_u32 v0, v6, v0
	v_mul_lo_u32 v4, v0, v3
	v_sub_u32_e32 v4, v6, v4
	v_add_u32_e32 v5, 1, v0
	v_cmp_ge_u32_e32 vcc, v4, v3
	s_nop 1
	v_cndmask_b32_e32 v0, v0, v5, vcc
	v_sub_u32_e32 v5, v4, v3
	v_cndmask_b32_e32 v4, v4, v5, vcc
	v_add_u32_e32 v5, 1, v0
	v_cmp_ge_u32_e32 vcc, v4, v3
	v_add_u32_e32 v4, 1, v6
	s_nop 0
	v_cndmask_b32_e32 v0, v0, v5, vcc
	v_mul_lo_u32 v5, v3, v0
	v_add_u32_e32 v3, v5, v3
	v_cmp_ne_u32_e32 vcc, v4, v3
	s_and_saveexec_b64 s[2:3], vcc
	s_xor_b64 s[2:3], exec, s[2:3]
	s_cbranch_execz .LBB0_123
	v_readlane_b32 s4, v253, 33
	v_readlane_b32 s5, v253, 34
	s_waitcnt lgkmcnt(0)
	s_nop 3
	global_load_dword v2, v1, s[4:5] sc1
	s_waitcnt vmcnt(0)
	v_cmp_eq_u32_e32 vcc, v2, v0
	s_and_saveexec_b64 s[4:5], vcc
	s_cbranch_execz .LBB0_122
	s_mov_b32 s16, 1
	s_mov_b64 s[6:7], 0
	s_branch .LBB0_113

; DI unsigned xb_ld(unsigned* p) { return __hip_atomic_load(p, __ATOMIC_RELAXED, __HIP_MEMORY_SCOPE_AGENT); }
; DI unsigned xb_add(unsigned* p, unsigned v) { return __hip_atomic_fetch_add(p, v, __ATOMIC_RELAXED, __HIP_MEMORY_SCOPE_AGENT); }
; #define XB_SPIN(cond, bar) do { unsigned _sp = 0; while (cond) { __builtin_amdgcn_s_sleep(1); \
;     if ((++_sp & 255u) == 0u) { if (xb_ld(&(bar)[XB_TMO])) break; if (_sp > XB_SPIN_CAP) { atomicAdd(&(bar)[XB_TMO], 1u); break; } } } } while (0)
; DI void xcd_barrier(const XcdBarrier& b) {
;     ...
;     const unsigned old = xb_add(&bar[XB_XSUB(b.x)], 1u);
;     const unsigned gen = old / nloc;
;     if (old + 1u == (gen + 1u) * nloc) {
;       __builtin_amdgcn_fence(__ATOMIC_RELEASE, "agent");
;       asm volatile("s_waitcnt vmcnt(0)" ::: "memory");
;       const unsigned og = xb_add(&bar[XB_TOP], 1u);
;       const unsigned tg = og / nx;
;       if (og + 1u == (tg + 1u) * nx) xb_add(&bar[XB_TOPGEN], 1u);
;       else XB_SPIN(xb_ld(&bar[XB_TOPGEN]) == tg, bar);
;       __builtin_amdgcn_fence(__ATOMIC_ACQUIRE, "agent");
;       xb_add(&bar[XB_XGEN(b.x)], 1u);
;       asm volatile("s_waitcnt vmcnt(0)" ::: "memory");
;     } else {
;       XB_SPIN(xb_ld(&bar[XB_XGEN(b.x)]) == gen, bar);
.LBB0_1019:
	s_or_b64 exec, exec, s[4:5]
	v_cvt_f32_u32_e32 v5, v3
	s_waitcnt vmcnt(0)
	v_readfirstlane_b32 s4, v4
	v_sub_u32_e32 v4, 0, v3
	v_rcp_iflag_f32_e32 v5, v5
	v_add_u32_e32 v6, s4, v0
	v_mul_f32_e32 v5, 0x4f7ffffe, v5
	v_cvt_u32_f32_e32 v5, v5
	v_mul_lo_u32 v0, v4, v5
	v_mul_hi_u32 v0, v5, v0
	v_add_u32_e32 v0, v5, v0
	v_mul_hi_u32 v0, v6, v0
	v_mul_lo_u32 v4, v0, v3
	v_sub_u32_e32 v4, v6, v4
	v_add_u32_e32 v5, 1, v0
	v_cmp_ge_u32_e32 vcc, v4, v3
	s_nop 1
	v_cndmask_b32_e32 v0, v0, v5, vcc
	v_sub_u32_e32 v5, v4, v3
	v_cndmask_b32_e32 v4, v4, v5, vcc
	v_add_u32_e32 v5, 1, v0
	v_cmp_ge_u32_e32 vcc, v4, v3
	v_add_u32_e32 v4, 1, v6
	s_nop 0
	v_cndmask_b32_e32 v0, v0, v5, vcc
	v_mul_lo_u32 v5, v3, v0
	v_add_u32_e32 v3, v5, v3
	v_cmp_ne_u32_e32 vcc, v4, v3
	s_and_saveexec_b64 s[4:5], vcc
	s_xor_b64 s[4:5], exec, s[4:5]
	s_cbranch_execz .LBB0_1033
	v_readlane_b32 s6, v253, 33
	v_readlane_b32 s7, v253, 34
	s_waitcnt lgkmcnt(0)
	s_nop 3
	global_load_dword v2, v1, s[6:7] sc1
	s_waitcnt vmcnt(0)
	v_cmp_eq_u32_e32 vcc, v2, v0
	s_and_saveexec_b64 s[6:7], vcc
	s_cbranch_execz .LBB0_1032
	s_mov_b32 s18, 1
	s_mov_b64 s[8:9], 0
	s_branch .LBB0_1023
